# P2: odd workgroups >= 64 run two gla_prep units before their rw_prep unit (memory-bound and VALU-bound pre-passes overlap)
# baseline (speedup 1.0000x reference)
; DEVINL int otid() { int t = threadIdx.x; asm volatile("" : "+v"(t)); return t; }
; DEVINL void phase2(const Params& p) {
;   const int bid = blockIdx.x, nb = gridDim.x, tid = otid();
;   for (int u = bid; u < 512; u += nb) gla_prep_unit(p, u);
;   for (int u = bid; u < 256; u += nb) rw_prep_unit(p, u);
; }
.Lq_skip:
	s_mov_b32 s99, -1
	s_cmp_lt_u32 s2, 64
	s_cbranch_scc1 .Lq_rwfirst
	s_bitcmp1_b32 s2, 0
	s_cbranch_scc0 .Lq_rwfirst
	s_mov_b32 s99, 2
	s_branch .LBB0_387

; DEVINL u16 f2bf(float a) { return (u16)(pk2(a, 0.f) & 0xffffu); }
; DEVINL float bf2f(u16 h) { return __uint_as_float(((unsigned)h) << 16); }
; DEVINL int fragpos(int idx) { const int w = idx & 31; return (idx & ~31) + (((w & 15) >> 2) << 3) + (w & 3) + ((w >> 4) << 2); }
; DEVINL void gla_prep_unit(const Params& p, int unit) {
;     ...
;       for (int j = 0; j < 8; ++j) {
;         const int i = i0 + j;
;         float bb = Gc[i * 128];
;         float q = bf2f(qv[j]);
;         float k = bf2f(kv[j]);
;         qt[i * 128] = f2bf(q * 0.08838834764831845f * __expf(bb));
;         kt[i * 128] = f2bf(k * __expf(-bb));
;         KDr[fragpos(i)] = f2bf(k * __expf(bedge - bb));
;       }
;     }
.Lgl_nodec:
	s_waitcnt lgkmcnt(0)
	s_barrier
	s_mov_b32 s56, 0x3db504f3
	ds_read_b128 v[116:119], v22 offset:0
	ds_read_b128 v[120:123], v22 offset:64
	ds_read_b64 v[124:125], v23 offset:0
	ds_read_b64 v[126:127], v23 offset:32
	s_waitcnt lgkmcnt(0)
	v_lshlrev_b32_e32 v128, 16, v124
	v_and_b32_e32 v129, 0xffff0000, v124
	v_lshlrev_b32_e32 v130, 16, v125
	v_and_b32_e32 v131, 0xffff0000, v125
	v_lshlrev_b32_e32 v132, 16, v126
	v_and_b32_e32 v133, 0xffff0000, v126
	v_lshlrev_b32_e32 v134, 16, v127
	v_and_b32_e32 v135, 0xffff0000, v127
	v_mul_f32_e32 v116, 0x3fb8aa3b, v116
	v_exp_f32_e32 v116, v116
	v_mul_f32_e32 v128, s56, v128
	v_mul_f32_e32 v128, v128, v116
	v_mul_f32_e32 v117, 0x3fb8aa3b, v117
	v_exp_f32_e32 v117, v117
	v_mul_f32_e32 v129, s56, v129
	v_mul_f32_e32 v129, v129, v117
	v_mul_f32_e32 v118, 0x3fb8aa3b, v118
	v_exp_f32_e32 v118, v118
	v_mul_f32_e32 v130, s56, v130
	v_mul_f32_e32 v130, v130, v118
	v_mul_f32_e32 v119, 0x3fb8aa3b, v119
	v_exp_f32_e32 v119, v119
	v_mul_f32_e32 v131, s56, v131
	v_mul_f32_e32 v131, v131, v119
	v_mul_f32_e32 v120, 0x3fb8aa3b, v120
	v_exp_f32_e32 v120, v120
	v_mul_f32_e32 v132, s56, v132
	v_mul_f32_e32 v132, v132, v120
	v_mul_f32_e32 v121, 0x3fb8aa3b, v121
	v_exp_f32_e32 v121, v121
	v_mul_f32_e32 v133, s56, v133
	v_mul_f32_e32 v133, v133, v121
	v_mul_f32_e32 v122, 0x3fb8aa3b, v122
	v_exp_f32_e32 v122, v122
	v_mul_f32_e32 v134, s56, v134
	v_mul_f32_e32 v134, v134, v122
	v_mul_f32_e32 v123, 0x3fb8aa3b, v123
	v_exp_f32_e32 v123, v123
	v_mul_f32_e32 v135, s56, v135
	v_mul_f32_e32 v135, v135, v123
	v_cvt_pk_bf16_f32 v140, v128, v129
	v_cvt_pk_bf16_f32 v141, v130, v131
	v_cvt_pk_bf16_f32 v142, v132, v133
	v_cvt_pk_bf16_f32 v143, v134, v135
	s_lshl_b32 s48, s43, 2
	s_add_u32 s48, s48, 0
	s_add_u32 s48, s48, s41
	s_lshl_b32 s48, s48, 20
	s_lshl_b32 s57, s42, 14
	s_add_u32 s48, s48, s57
	s_add_u32 s48, s48, 0
	s_add_u32 s58, s92, s48
	s_addc_u32 s59, s93, 0
	s_add_u32 s58, s58, 0x17400000
	s_addc_u32 s59, s59, 0
	global_store_dwordx4 v2, v[140:143], s[58:59] nt
	ds_read_b128 v[116:119], v22 offset:16384
	ds_read_b128 v[120:123], v22 offset:16448
	ds_read_b64 v[124:125], v23 offset:8192
	ds_read_b64 v[126:127], v23 offset:8224
	s_waitcnt lgkmcnt(0)
	v_lshlrev_b32_e32 v128, 16, v124
	v_and_b32_e32 v129, 0xffff0000, v124
	v_lshlrev_b32_e32 v130, 16, v125
	v_and_b32_e32 v131, 0xffff0000, v125
	v_lshlrev_b32_e32 v132, 16, v126
	v_and_b32_e32 v133, 0xffff0000, v126
	v_lshlrev_b32_e32 v134, 16, v127
	v_and_b32_e32 v135, 0xffff0000, v127
	v_mul_f32_e32 v116, 0x3fb8aa3b, v116
	v_exp_f32_e32 v116, v116
	v_mul_f32_e32 v128, s56, v128
	v_mul_f32_e32 v128, v128, v116
	v_mul_f32_e32 v117, 0x3fb8aa3b, v117
	v_exp_f32_e32 v117, v117
	v_mul_f32_e32 v129, s56, v129
	v_mul_f32_e32 v129, v129, v117
	v_mul_f32_e32 v118, 0x3fb8aa3b, v118
	v_exp_f32_e32 v118, v118
	v_mul_f32_e32 v130, s56, v130
	v_mul_f32_e32 v130, v130, v118
	v_mul_f32_e32 v119, 0x3fb8aa3b, v119
	v_exp_f32_e32 v119, v119
	v_mul_f32_e32 v131, s56, v131
	v_mul_f32_e32 v131, v131, v119
	v_mul_f32_e32 v120, 0x3fb8aa3b, v120
	v_exp_f32_e32 v120, v120
	v_mul_f32_e32 v132, s56, v132
	v_mul_f32_e32 v132, v132, v120
	v_mul_f32_e32 v121, 0x3fb8aa3b, v121
	v_exp_f32_e32 v121, v121
	v_mul_f32_e32 v133, s56, v133
	v_mul_f32_e32 v133, v133, v121
	v_mul_f32_e32 v122, 0x3fb8aa3b, v122
	v_exp_f32_e32 v122, v122
	v_mul_f32_e32 v134, s56, v134
	v_mul_f32_e32 v134, v134, v122
	v_mul_f32_e32 v123, 0x3fb8aa3b, v123
	v_exp_f32_e32 v123, v123
	v_mul_f32_e32 v135, s56, v135
	v_mul_f32_e32 v135, v135, v123
	v_cvt_pk_bf16_f32 v140, v128, v129
	v_cvt_pk_bf16_f32 v141, v130, v131
	v_cvt_pk_bf16_f32 v142, v132, v133
	v_cvt_pk_bf16_f32 v143, v134, v135
	s_lshl_b32 s48, s43, 2
	s_add_u32 s48, s48, 0
	s_add_u32 s48, s48, s41
	s_lshl_b32 s48, s48, 20
	s_lshl_b32 s57, s42, 14
	s_add_u32 s48, s48, s57
	s_add_u32 s48, s48, 8192
	s_add_u32 s58, s92, s48
	s_addc_u32 s59, s93, 0
	s_add_u32 s58, s58, 0x17400000
	s_addc_u32 s59, s59, 0
	global_store_dwordx4 v2, v[140:143], s[58:59] nt
	ds_read_b128 v[116:119], v22 offset:0
	ds_read_b128 v[120:123], v22 offset:64
	ds_read_b64 v[124:125], v23 offset:16384
	ds_read_b64 v[126:127], v23 offset:16416
	s_waitcnt lgkmcnt(0)
	v_lshlrev_b32_e32 v128, 16, v124
	v_and_b32_e32 v129, 0xffff0000, v124
	v_lshlrev_b32_e32 v130, 16, v125
	v_and_b32_e32 v131, 0xffff0000, v125
	v_lshlrev_b32_e32 v132, 16, v126
	v_and_b32_e32 v133, 0xffff0000, v126
	v_lshlrev_b32_e32 v134, 16, v127
	v_and_b32_e32 v135, 0xffff0000, v127
	v_mul_f32_e32 v116, 0xbfb8aa3b, v116
	v_exp_f32_e32 v116, v116
	s_nop 0
	v_mul_f32_e32 v128, v116, v128
	v_mul_f32_e32 v117, 0xbfb8aa3b, v117
	v_exp_f32_e32 v117, v117
	s_nop 0
	v_mul_f32_e32 v129, v117, v129
	v_mul_f32_e32 v118, 0xbfb8aa3b, v118
	v_exp_f32_e32 v118, v118
	s_nop 0
	v_mul_f32_e32 v130, v118, v130
	v_mul_f32_e32 v119, 0xbfb8aa3b, v119
	v_exp_f32_e32 v119, v119
	s_nop 0
	v_mul_f32_e32 v131, v119, v131
	v_mul_f32_e32 v120, 0xbfb8aa3b, v120
	v_exp_f32_e32 v120, v120
	s_nop 0
	v_mul_f32_e32 v132, v120, v132
	v_mul_f32_e32 v121, 0xbfb8aa3b, v121
	v_exp_f32_e32 v121, v121
	s_nop 0
	v_mul_f32_e32 v133, v121, v133
	v_mul_f32_e32 v122, 0xbfb8aa3b, v122
	v_exp_f32_e32 v122, v122
	s_nop 0
	v_mul_f32_e32 v134, v122, v134
	v_mul_f32_e32 v123, 0xbfb8aa3b, v123
	v_exp_f32_e32 v123, v123
	s_nop 0
	v_mul_f32_e32 v135, v123, v135
	v_cvt_pk_bf16_f32 v140, v128, v129
	v_cvt_pk_bf16_f32 v141, v130, v131
	v_cvt_pk_bf16_f32 v142, v132, v133
	v_cvt_pk_bf16_f32 v143, v134, v135
	s_lshl_b32 s48, s43, 2
	s_add_u32 s48, s48, 0
	s_add_u32 s48, s48, s41
	s_lshl_b32 s48, s48, 20
	s_lshl_b32 s57, s42, 14
	s_add_u32 s48, s48, s57
	s_add_u32 s48, s48, 0
	s_add_u32 s58, s92, s48
	s_addc_u32 s59, s93, 0
	s_add_u32 s58, s58, 0x18400000
	s_addc_u32 s59, s59, 0
	global_store_dwordx4 v2, v[140:143], s[58:59] nt
	ds_read_b128 v[116:119], v22 offset:16384
	ds_read_b128 v[120:123], v22 offset:16448
	ds_read_b64 v[124:125], v23 offset:24576
	ds_read_b64 v[126:127], v23 offset:24608
	s_waitcnt lgkmcnt(0)
; DEVINL u16 f2bf(float a) { return (u16)(pk2(a, 0.f) & 0xffffu); }
; DEVINL float bf2f(u16 h) { return __uint_as_float(((unsigned)h) << 16); }
; DEVINL int fragpos(int idx) { const int w = idx & 31; return (idx & ~31) + (((w & 15) >> 2) << 3) + (w & 3) + ((w >> 4) << 2); }
; DEVINL void gla_prep_unit(const Params& p, int unit) {
;     ...
;       for (int j = 0; j < 8; ++j) {
;         const int i = i0 + j;
;         float bb = Gc[i * 128];
;         float q = bf2f(qv[j]);
;         float k = bf2f(kv[j]);
;         qt[i * 128] = f2bf(q * 0.08838834764831845f * __expf(bb));
;         kt[i * 128] = f2bf(k * __expf(-bb));
;         KDr[fragpos(i)] = f2bf(k * __expf(bedge - bb));
;       }
;     }
	v_lshlrev_b32_e32 v128, 16, v124
	v_and_b32_e32 v129, 0xffff0000, v124
	v_lshlrev_b32_e32 v130, 16, v125
	v_and_b32_e32 v131, 0xffff0000, v125
	v_lshlrev_b32_e32 v132, 16, v126
	v_and_b32_e32 v133, 0xffff0000, v126
	v_lshlrev_b32_e32 v134, 16, v127
	v_and_b32_e32 v135, 0xffff0000, v127
	v_mul_f32_e32 v116, 0xbfb8aa3b, v116
	v_exp_f32_e32 v116, v116
	s_nop 0
	v_mul_f32_e32 v128, v116, v128
	v_mul_f32_e32 v117, 0xbfb8aa3b, v117
	v_exp_f32_e32 v117, v117
	s_nop 0
	v_mul_f32_e32 v129, v117, v129
	v_mul_f32_e32 v118, 0xbfb8aa3b, v118
	v_exp_f32_e32 v118, v118
	s_nop 0
	v_mul_f32_e32 v130, v118, v130
	v_mul_f32_e32 v119, 0xbfb8aa3b, v119
	v_exp_f32_e32 v119, v119
	s_nop 0
	v_mul_f32_e32 v131, v119, v131
	v_mul_f32_e32 v120, 0xbfb8aa3b, v120
	v_exp_f32_e32 v120, v120
	s_nop 0
	v_mul_f32_e32 v132, v120, v132
	v_mul_f32_e32 v121, 0xbfb8aa3b, v121
	v_exp_f32_e32 v121, v121
	s_nop 0
	v_mul_f32_e32 v133, v121, v133
	v_mul_f32_e32 v122, 0xbfb8aa3b, v122
	v_exp_f32_e32 v122, v122
	s_nop 0
	v_mul_f32_e32 v134, v122, v134
	v_mul_f32_e32 v123, 0xbfb8aa3b, v123
	v_exp_f32_e32 v123, v123
	s_nop 0
	v_mul_f32_e32 v135, v123, v135
	v_cvt_pk_bf16_f32 v140, v128, v129
	v_cvt_pk_bf16_f32 v141, v130, v131
	v_cvt_pk_bf16_f32 v142, v132, v133
	v_cvt_pk_bf16_f32 v143, v134, v135
	s_lshl_b32 s48, s43, 2
	s_add_u32 s48, s48, 0
	s_add_u32 s48, s48, s41
	s_lshl_b32 s48, s48, 20
	s_lshl_b32 s57, s42, 14
	s_add_u32 s48, s48, s57
	s_add_u32 s48, s48, 8192
	s_add_u32 s58, s92, s48
	s_addc_u32 s59, s93, 0
	s_add_u32 s58, s58, 0x18400000
	s_addc_u32 s59, s59, 0
	global_store_dwordx4 v2, v[140:143], s[58:59] nt
	ds_read_b128 v[116:119], v22 offset:32768
	ds_read_b128 v[120:123], v22 offset:32832
	ds_read_b64 v[124:125], v23 offset:0
	ds_read_b64 v[126:127], v23 offset:32
	s_waitcnt lgkmcnt(0)
	v_lshlrev_b32_e32 v128, 16, v124
	v_and_b32_e32 v129, 0xffff0000, v124
	v_lshlrev_b32_e32 v130, 16, v125
	v_and_b32_e32 v131, 0xffff0000, v125
	v_lshlrev_b32_e32 v132, 16, v126
	v_and_b32_e32 v133, 0xffff0000, v126
	v_lshlrev_b32_e32 v134, 16, v127
	v_and_b32_e32 v135, 0xffff0000, v127
	v_mul_f32_e32 v116, 0x3fb8aa3b, v116
	v_exp_f32_e32 v116, v116
	v_mul_f32_e32 v128, s56, v128
	v_mul_f32_e32 v128, v128, v116
	v_mul_f32_e32 v117, 0x3fb8aa3b, v117
	v_exp_f32_e32 v117, v117
	v_mul_f32_e32 v129, s56, v129
	v_mul_f32_e32 v129, v129, v117
	v_mul_f32_e32 v118, 0x3fb8aa3b, v118
	v_exp_f32_e32 v118, v118
	v_mul_f32_e32 v130, s56, v130
	v_mul_f32_e32 v130, v130, v118
	v_mul_f32_e32 v119, 0x3fb8aa3b, v119
	v_exp_f32_e32 v119, v119
	v_mul_f32_e32 v131, s56, v131
	v_mul_f32_e32 v131, v131, v119
	v_mul_f32_e32 v120, 0x3fb8aa3b, v120
	v_exp_f32_e32 v120, v120
	v_mul_f32_e32 v132, s56, v132
	v_mul_f32_e32 v132, v132, v120
	v_mul_f32_e32 v121, 0x3fb8aa3b, v121
	v_exp_f32_e32 v121, v121
	v_mul_f32_e32 v133, s56, v133
	v_mul_f32_e32 v133, v133, v121
	v_mul_f32_e32 v122, 0x3fb8aa3b, v122
	v_exp_f32_e32 v122, v122
	v_mul_f32_e32 v134, s56, v134
	v_mul_f32_e32 v134, v134, v122
	v_mul_f32_e32 v123, 0x3fb8aa3b, v123
	v_exp_f32_e32 v123, v123
	v_mul_f32_e32 v135, s56, v135
	v_mul_f32_e32 v135, v135, v123
	v_cvt_pk_bf16_f32 v140, v128, v129
	v_cvt_pk_bf16_f32 v141, v130, v131
	v_cvt_pk_bf16_f32 v142, v132, v133
	v_cvt_pk_bf16_f32 v143, v134, v135
	s_lshl_b32 s48, s43, 2
	s_add_u32 s48, s48, 8
	s_add_u32 s48, s48, s41
	s_lshl_b32 s48, s48, 20
	s_lshl_b32 s57, s42, 14
	s_add_u32 s48, s48, s57
	s_add_u32 s48, s48, 0
	s_add_u32 s58, s92, s48
	s_addc_u32 s59, s93, 0
	s_add_u32 s58, s58, 0x17400000
	s_addc_u32 s59, s59, 0
	global_store_dwordx4 v2, v[140:143], s[58:59] nt
	ds_read_b128 v[116:119], v22 offset:49152
	ds_read_b128 v[120:123], v22 offset:49216
	ds_read_b64 v[124:125], v23 offset:8192
	ds_read_b64 v[126:127], v23 offset:8224
	s_waitcnt lgkmcnt(0)
; DEVINL u16 f2bf(float a) { return (u16)(pk2(a, 0.f) & 0xffffu); }
; DEVINL float bf2f(u16 h) { return __uint_as_float(((unsigned)h) << 16); }
; DEVINL int fragpos(int idx) { const int w = idx & 31; return (idx & ~31) + (((w & 15) >> 2) << 3) + (w & 3) + ((w >> 4) << 2); }
; DEVINL void gla_prep_unit(const Params& p, int unit) {
;     ...
;     for (int i0 = 0; i0 < 64; i0 += 8) {
;       u16 qv[8], kv[8];
; #pragma unroll
;       for (int j = 0; j < 8; ++j) { qv[j] = qsrc[(long)(i0 + j) * NCP]; kv[j] = ksrc[(long)(i0 + j) * NCP]; }
; #pragma unroll
;       for (int j = 0; j < 8; ++j) {
;         const int i = i0 + j;
;         float bb = Gc[i * 128];
;         float q = bf2f(qv[j]);
;         float k = bf2f(kv[j]);
;         qt[i * 128] = f2bf(q * 0.08838834764831845f * __expf(bb));
;         kt[i * 128] = f2bf(k * __expf(-bb));
;         KDr[fragpos(i)] = f2bf(k * __expf(bedge - bb));
;       }
;     }
	v_lshlrev_b32_e32 v128, 16, v124
	v_and_b32_e32 v129, 0xffff0000, v124
	v_lshlrev_b32_e32 v130, 16, v125
	v_and_b32_e32 v131, 0xffff0000, v125
	v_lshlrev_b32_e32 v132, 16, v126
	v_and_b32_e32 v133, 0xffff0000, v126
	v_lshlrev_b32_e32 v134, 16, v127
	v_and_b32_e32 v135, 0xffff0000, v127
	v_mul_f32_e32 v116, 0x3fb8aa3b, v116
	v_exp_f32_e32 v116, v116
	v_mul_f32_e32 v128, s56, v128
	v_mul_f32_e32 v128, v128, v116
	v_mul_f32_e32 v117, 0x3fb8aa3b, v117
	v_exp_f32_e32 v117, v117
	v_mul_f32_e32 v129, s56, v129
	v_mul_f32_e32 v129, v129, v117
	v_mul_f32_e32 v118, 0x3fb8aa3b, v118
	v_exp_f32_e32 v118, v118
	v_mul_f32_e32 v130, s56, v130
	v_mul_f32_e32 v130, v130, v118
	v_mul_f32_e32 v119, 0x3fb8aa3b, v119
	v_exp_f32_e32 v119, v119
	v_mul_f32_e32 v131, s56, v131
	v_mul_f32_e32 v131, v131, v119
	v_mul_f32_e32 v120, 0x3fb8aa3b, v120
	v_exp_f32_e32 v120, v120
	v_mul_f32_e32 v132, s56, v132
	v_mul_f32_e32 v132, v132, v120
	v_mul_f32_e32 v121, 0x3fb8aa3b, v121
	v_exp_f32_e32 v121, v121
	v_mul_f32_e32 v133, s56, v133
	v_mul_f32_e32 v133, v133, v121
	v_mul_f32_e32 v122, 0x3fb8aa3b, v122
	v_exp_f32_e32 v122, v122
	v_mul_f32_e32 v134, s56, v134
	v_mul_f32_e32 v134, v134, v122
	v_mul_f32_e32 v123, 0x3fb8aa3b, v123
	v_exp_f32_e32 v123, v123
	v_mul_f32_e32 v135, s56, v135
	v_mul_f32_e32 v135, v135, v123
	v_cvt_pk_bf16_f32 v140, v128, v129
	v_cvt_pk_bf16_f32 v141, v130, v131
	v_cvt_pk_bf16_f32 v142, v132, v133
	v_cvt_pk_bf16_f32 v143, v134, v135
	s_lshl_b32 s48, s43, 2
	s_add_u32 s48, s48, 8
	s_add_u32 s48, s48, s41
	s_lshl_b32 s48, s48, 20
	s_lshl_b32 s57, s42, 14
	s_add_u32 s48, s48, s57
	s_add_u32 s48, s48, 8192
	s_add_u32 s58, s92, s48
	s_addc_u32 s59, s93, 0
	s_add_u32 s58, s58, 0x17400000
	s_addc_u32 s59, s59, 0
	global_store_dwordx4 v2, v[140:143], s[58:59] nt
	ds_read_b128 v[116:119], v22 offset:32768
	ds_read_b128 v[120:123], v22 offset:32832
	ds_read_b64 v[124:125], v23 offset:16384
	ds_read_b64 v[126:127], v23 offset:16416
	s_waitcnt lgkmcnt(0)
	v_lshlrev_b32_e32 v128, 16, v124
	v_and_b32_e32 v129, 0xffff0000, v124
	v_lshlrev_b32_e32 v130, 16, v125
	v_and_b32_e32 v131, 0xffff0000, v125
	v_lshlrev_b32_e32 v132, 16, v126
	v_and_b32_e32 v133, 0xffff0000, v126
	v_lshlrev_b32_e32 v134, 16, v127
	v_and_b32_e32 v135, 0xffff0000, v127
	v_mul_f32_e32 v116, 0xbfb8aa3b, v116
	v_exp_f32_e32 v116, v116
	s_nop 0
	v_mul_f32_e32 v128, v116, v128
	v_mul_f32_e32 v117, 0xbfb8aa3b, v117
	v_exp_f32_e32 v117, v117
	s_nop 0
	v_mul_f32_e32 v129, v117, v129
	v_mul_f32_e32 v118, 0xbfb8aa3b, v118
	v_exp_f32_e32 v118, v118
	s_nop 0
	v_mul_f32_e32 v130, v118, v130
	v_mul_f32_e32 v119, 0xbfb8aa3b, v119
	v_exp_f32_e32 v119, v119
	s_nop 0
	v_mul_f32_e32 v131, v119, v131
	v_mul_f32_e32 v120, 0xbfb8aa3b, v120
	v_exp_f32_e32 v120, v120
	s_nop 0
	v_mul_f32_e32 v132, v120, v132
	v_mul_f32_e32 v121, 0xbfb8aa3b, v121
	v_exp_f32_e32 v121, v121
	s_nop 0
	v_mul_f32_e32 v133, v121, v133
	v_mul_f32_e32 v122, 0xbfb8aa3b, v122
	v_exp_f32_e32 v122, v122
	s_nop 0
	v_mul_f32_e32 v134, v122, v134
	v_mul_f32_e32 v123, 0xbfb8aa3b, v123
	v_exp_f32_e32 v123, v123
	s_nop 0
	v_mul_f32_e32 v135, v123, v135
	v_cvt_pk_bf16_f32 v140, v128, v129
	v_cvt_pk_bf16_f32 v141, v130, v131
	v_cvt_pk_bf16_f32 v142, v132, v133
	v_cvt_pk_bf16_f32 v143, v134, v135
	s_lshl_b32 s48, s43, 2
	s_add_u32 s48, s48, 8
	s_add_u32 s48, s48, s41
	s_lshl_b32 s48, s48, 20
	s_lshl_b32 s57, s42, 14
	s_add_u32 s48, s48, s57
	s_add_u32 s48, s48, 0
	s_add_u32 s58, s92, s48
	s_addc_u32 s59, s93, 0
	s_add_u32 s58, s58, 0x18400000
	s_addc_u32 s59, s59, 0
	global_store_dwordx4 v2, v[140:143], s[58:59] nt
	ds_read_b128 v[116:119], v22 offset:49152
	ds_read_b128 v[120:123], v22 offset:49216
	ds_read_b64 v[124:125], v23 offset:24576
	ds_read_b64 v[126:127], v23 offset:24608
	s_waitcnt lgkmcnt(0)
	v_lshlrev_b32_e32 v128, 16, v124
	v_and_b32_e32 v129, 0xffff0000, v124
	v_lshlrev_b32_e32 v130, 16, v125
	v_and_b32_e32 v131, 0xffff0000, v125
	v_lshlrev_b32_e32 v132, 16, v126
	v_and_b32_e32 v133, 0xffff0000, v126
	v_lshlrev_b32_e32 v134, 16, v127
	v_and_b32_e32 v135, 0xffff0000, v127
	v_mul_f32_e32 v116, 0xbfb8aa3b, v116
	v_exp_f32_e32 v116, v116
	s_nop 0
	v_mul_f32_e32 v128, v116, v128
	v_mul_f32_e32 v117, 0xbfb8aa3b, v117
	v_exp_f32_e32 v117, v117
	s_nop 0
	v_mul_f32_e32 v129, v117, v129
	v_mul_f32_e32 v118, 0xbfb8aa3b, v118
	v_exp_f32_e32 v118, v118
	s_nop 0
	v_mul_f32_e32 v130, v118, v130
	v_mul_f32_e32 v119, 0xbfb8aa3b, v119
	v_exp_f32_e32 v119, v119
	s_nop 0
	v_mul_f32_e32 v131, v119, v131
	v_mul_f32_e32 v120, 0xbfb8aa3b, v120
	v_exp_f32_e32 v120, v120
	s_nop 0
	v_mul_f32_e32 v132, v120, v132
	v_mul_f32_e32 v121, 0xbfb8aa3b, v121
	v_exp_f32_e32 v121, v121
	s_nop 0
	v_mul_f32_e32 v133, v121, v133
	v_mul_f32_e32 v122, 0xbfb8aa3b, v122
	v_exp_f32_e32 v122, v122
	s_nop 0
	v_mul_f32_e32 v134, v122, v134
	v_mul_f32_e32 v123, 0xbfb8aa3b, v123
	v_exp_f32_e32 v123, v123
	s_nop 0
	v_mul_f32_e32 v135, v123, v135
	v_cvt_pk_bf16_f32 v140, v128, v129
	v_cvt_pk_bf16_f32 v141, v130, v131
	v_cvt_pk_bf16_f32 v142, v132, v133
	v_cvt_pk_bf16_f32 v143, v134, v135
	s_lshl_b32 s48, s43, 2
	s_add_u32 s48, s48, 8
	s_add_u32 s48, s48, s41
	s_lshl_b32 s48, s48, 20
	s_lshl_b32 s57, s42, 14
	s_add_u32 s48, s48, s57
	s_add_u32 s48, s48, 8192
	s_add_u32 s58, s92, s48
	s_addc_u32 s59, s93, 0
	s_add_u32 s58, s58, 0x18400000
	s_addc_u32 s59, s59, 0
	global_store_dwordx4 v2, v[140:143], s[58:59] nt
	s_cmp_lt_i32 s99, 1
	s_cbranch_scc1 .Lgl_unit
	s_sub_u32 s99, s99, 1
	s_cmp_lg_u32 s99, 0
	s_cbranch_scc1 .Lgl_unit
	s_mov_b32 s99, -1
	s_branch .Lq_rwfirst

; #define LAS __attribute__((address_space(3)))
; __global__ void __launch_bounds__(512, 2) k_mega(Params p) {
;   cg::grid_group grid = cg::this_grid();
;   __shared__ uint4 xb_words;
;   unsigned* bar = (unsigned*)(p.ws + O_BAR);
;   if (threadIdx.x == 0) xb_words = make_uint4(0u, 0u, 0u, 0u);
;   __syncthreads();
;   XcdBarrier xb = xcd_barrier_post(bar, (volatile LAS unsigned*)&xb_words);
;   if (p.out == nullptr) grid.sync();
;   run_phase<0>(p); xcd_barrier(xb);
;   run_phase<1>(p); xcd_barrier(xb);
;   run_phase<2>(p); xcd_barrier(xb);
;   run_phase<3>(p); xcd_barrier(xb);
;   run_phase<4>(p); xcd_barrier(xb);
;   run_phase<5>(p); xcd_barrier(xb);
;   run_phase<6>(p); xcd_barrier(xb);
;   run_phase<7>(p); xcd_barrier(xb);
;   run_phase<8>(p); xcd_barrier(xb);
;   run_phase<9>(p); xcd_barrier(xb);
;   run_phase<10>(p); xcd_barrier(xb);
;   run_phase<11>(p);
; }
	.amdhsa_kernel _Z6k_mega6Params
		.amdhsa_group_segment_fixed_size 8208
		.amdhsa_private_segment_fixed_size 0
		.amdhsa_kernarg_size 520
		.amdhsa_user_sgpr_count 2
		.amdhsa_user_sgpr_dispatch_ptr 0
		.amdhsa_user_sgpr_queue_ptr 0
		.amdhsa_user_sgpr_kernarg_segment_ptr 1
		.amdhsa_user_sgpr_dispatch_id 0
		.amdhsa_user_sgpr_kernarg_preload_length 0
		.amdhsa_user_sgpr_kernarg_preload_offset 0
		.amdhsa_user_sgpr_private_segment_size 0
		.amdhsa_uses_dynamic_stack 0
		.amdhsa_enable_private_segment 0
		.amdhsa_system_sgpr_workgroup_id_x 1
		.amdhsa_system_sgpr_workgroup_id_y 0
		.amdhsa_system_sgpr_workgroup_id_z 0
		.amdhsa_system_sgpr_workgroup_info 0
		.amdhsa_system_vgpr_workitem_id 2
		.amdhsa_next_free_vgpr 256
		.amdhsa_next_free_sgpr 100
		.amdhsa_accum_offset 256
		.amdhsa_reserve_vcc 1
		.amdhsa_float_round_mode_32 0
		.amdhsa_float_round_mode_16_64 0
		.amdhsa_float_denorm_mode_32 3
		.amdhsa_float_denorm_mode_16_64 3
		.amdhsa_dx10_clamp 1
		.amdhsa_ieee_mode 1
		.amdhsa_fp16_overflow 0
		.amdhsa_tg_split 0
		.amdhsa_exception_fp_ieee_invalid_op 0
		.amdhsa_exception_fp_denorm_src 0
		.amdhsa_exception_fp_ieee_div_zero 0
		.amdhsa_exception_fp_ieee_overflow 0
		.amdhsa_exception_fp_ieee_underflow 0
		.amdhsa_exception_fp_ieee_inexact 0
		.amdhsa_exception_int_div_zero 0
	.end_amdhsa_kernel

; #define LAS __attribute__((address_space(3)))
; __global__ void __launch_bounds__(512, 2) k_mega(Params p) {
;   cg::grid_group grid = cg::this_grid();
;   __shared__ uint4 xb_words;
;   unsigned* bar = (unsigned*)(p.ws + O_BAR);
;   if (threadIdx.x == 0) xb_words = make_uint4(0u, 0u, 0u, 0u);
;   __syncthreads();
;   XcdBarrier xb = xcd_barrier_post(bar, (volatile LAS unsigned*)&xb_words);
;   if (p.out == nullptr) grid.sync();
;   run_phase<0>(p); xcd_barrier(xb);
;   run_phase<1>(p); xcd_barrier(xb);
;   run_phase<2>(p); xcd_barrier(xb);
;   run_phase<3>(p); xcd_barrier(xb);
;   run_phase<4>(p); xcd_barrier(xb);
;   run_phase<5>(p); xcd_barrier(xb);
;   run_phase<6>(p); xcd_barrier(xb);
;   run_phase<7>(p); xcd_barrier(xb);
;   run_phase<8>(p); xcd_barrier(xb);
;   run_phase<9>(p); xcd_barrier(xb);
;   run_phase<10>(p); xcd_barrier(xb);
;   run_phase<11>(p);
; }
amdhsa.kernels:
  - .agpr_count:     0
    .args:
      - .offset:         0
        .size:           264
        .value_kind:     by_value
      - .offset:         264
        .size:           4
        .value_kind:     hidden_block_count_x
      - .offset:         268
        .size:           4
        .value_kind:     hidden_block_count_y
      - .offset:         272
        .size:           4
        .value_kind:     hidden_block_count_z
      - .offset:         276
        .size:           2
        .value_kind:     hidden_group_size_x
      - .offset:         278
        .size:           2
        .value_kind:     hidden_group_size_y
      - .offset:         280
        .size:           2
        .value_kind:     hidden_group_size_z
      - .offset:         282
        .size:           2
        .value_kind:     hidden_remainder_x
      - .offset:         284
        .size:           2
        .value_kind:     hidden_remainder_y
      - .offset:         286
        .size:           2
        .value_kind:     hidden_remainder_z
      - .offset:         304
        .size:           8
        .value_kind:     hidden_global_offset_x
      - .offset:         312
        .size:           8
        .value_kind:     hidden_global_offset_y
      - .offset:         320
        .size:           8
        .value_kind:     hidden_global_offset_z
      - .offset:         328
        .size:           2
        .value_kind:     hidden_grid_dims
      - .offset:         352
        .size:           8
        .value_kind:     hidden_multigrid_sync_arg
      - .offset:         384
        .size:           4
        .value_kind:     hidden_dynamic_lds_size
    .group_segment_fixed_size: 8208
    .kernarg_segment_align: 8
    .kernarg_segment_size: 520
    .language:       OpenCL C
    .language_version:
      - 2
      - 0
    .max_flat_workgroup_size: 512
    .name:           _Z6k_mega6Params
    .private_segment_fixed_size: 0
    .sgpr_count:     106
    .sgpr_spill_count: 20
    .symbol:         _Z6k_mega6Params.kd
    .uniform_work_group_size: 1
    .uses_dynamic_stack: false
    .vgpr_count:     256
    .vgpr_spill_count: 0
    .wavefront_size: 64
